# fused indexer/attention loop: one static s_setprio 1 for waves 4-7, per-burst priority flips removed
# baseline (speedup 1.0000x reference)
; __global__ void __launch_bounds__(512, 2) mk_fwd(Args a) {
;     ...
;             for (;;) {
;                 if (tid == 0) *slot = (int)__hip_atomic_fetch_add(qc, 1u, __ATOMIC_RELAXED, __HIP_MEMORY_SCOPE_AGENT);
;                 __syncthreads();
;                 const int j = __builtin_amdgcn_readfirstlane(*slot);
;                 if (j >= 128) break;
;                 const int bb = 2 * x + (j & 1), qb = 63 - (j >> 1);
;                 _Pragma("unroll 1") for (int hf = 0; hf < 2; ++hf) { int tu = threadIdx.x; asm volatile("" : "+v"(tu)); indexer_unit(a5, lds, maskl + hf * 512, bb, 2 * qb + hf, wave, tu & 63); }
;                 { int tu = threadIdx.x; asm volatile("" : "+v"(tu)); dsa_unit32(a5, lds, maskl, bb, qb, tu, wave, tu & 63); }
.Ldq_prime_skip:
	s_mov_b64 exec, s[20:21]
	s_cmp_ge_u32 s85, 8
	s_cbranch_scc0 .Lprio_done
	s_setprio 1

; #define GAS __attribute__((address_space(1)))
; __device__ __forceinline__ f32x4 mfma16(bf16x8 a, bf16x8 b, f32x4 c) { return __builtin_amdgcn_mfma_f32_16x16x32_bf16(a, b, c, 0, 0, 0); }
; __device__ __forceinline__ void indexer_unit(const Args& a, LAS unsigned char* lds, LAS unsigned long long* maskl, int b, int qblk, int wave, int lane) {
;     ...
;     for (int kt = wave; kt < nkt; kt += 8) {
;         const int key = 16 * kt + fr;
;         const bf16x8 b0 = nb0, b1 = nb1;
;         { const int k2 = kt + 8 < nkt ? kt + 8 : kt; const GAS bf16* p = ikn + (rowb + 16 * k2 + fr) * 64 + 8 * fq; nb0 = *(const GAS bf16x8*)p; nb1 = *(const GAS bf16x8*)(p + 32); }
; #pragma unroll
;         for (int rt = 0; rt < 8; ++rt) {
;             f32x4 acc = {0.f, 0.f, 0.f, 0.f};
;             __builtin_amdgcn_s_setprio(1); acc = mfma16(af[rt][0], b0, acc); acc = mfma16(af[rt][1], b1, acc); __builtin_amdgcn_s_setprio(0);
;             float part = wv[rt][0] * fmaxf(acc[0], 0.f) + wv[rt][1] * fmaxf(acc[1], 0.f) + wv[rt][2] * fmaxf(acc[2], 0.f) + wv[rt][3] * fmaxf(acc[3], 0.f);
;             part += __shfl_xor(part, 16); part += 0.f;
;             if ((fq & 1) == 0) sc[(2 * rt + (fq >> 1)) * 2048 + key] = part;
;         }
.LBB0_1085:
	s_mov_b32 s11, s10
	s_add_i32 s10, s10, 8
	s_cmp_gt_u32 s10, s9
	s_cselect_b64 s[2:3], -1, 0
	s_and_b64 s[4:5], s[2:3], exec
	s_cselect_b32 s4, s11, s10
	v_lshl_add_u32 v74, s4, 4, v117
	v_mov_b32_e32 v75, v4
	v_lshlrev_b64 v[74:75], 7, v[74:75]
	v_lshl_add_u64 v[78:79], v[82:83], 0, v[74:75]
	global_load_dwordx4 v[74:77], v[78:79], off
	s_nop 0
	global_load_dwordx4 v[78:81], v[78:79], off offset:64
	v_mfma_f32_16x16x32_bf16 v[128:131], v[0:3], v[70:73], 0
	v_mfma_f32_16x16x32_bf16 v[132:135], v[14:17], v[70:73], 0
	v_mfma_f32_16x16x32_bf16 v[136:139], v[18:21], v[70:73], 0
	v_mfma_f32_16x16x32_bf16 v[140:143], v[30:33], v[70:73], 0
	v_mfma_f32_16x16x32_bf16 v[144:147], v[34:37], v[70:73], 0
	v_mfma_f32_16x16x32_bf16 v[148:151], v[42:45], v[70:73], 0
	v_mfma_f32_16x16x32_bf16 v[152:155], v[54:57], v[70:73], 0
	v_mfma_f32_16x16x32_bf16 v[156:159], v[46:49], v[70:73], 0
	v_mfma_f32_16x16x32_bf16 v[128:131], v[6:9], v[66:69], v[128:131]
	v_mfma_f32_16x16x32_bf16 v[132:135], v[10:13], v[66:69], v[132:135]
	v_mfma_f32_16x16x32_bf16 v[136:139], v[22:25], v[66:69], v[136:139]
	v_mfma_f32_16x16x32_bf16 v[140:143], v[26:29], v[66:69], v[140:143]
	v_mfma_f32_16x16x32_bf16 v[144:147], v[38:41], v[66:69], v[144:147]
	v_mfma_f32_16x16x32_bf16 v[148:151], v[50:53], v[66:69], v[148:151]
	v_mfma_f32_16x16x32_bf16 v[152:155], v[58:61], v[66:69], v[152:155]
	v_mfma_f32_16x16x32_bf16 v[156:159], v[62:65], v[66:69], v[156:159]
	s_nop 1
	v_max_f32_e32 v160, 0, v128
	v_max_f32_e32 v168, 0, v129
	v_fma_f32 v168, v168, v86, 0
	v_max_f32_e32 v161, 0, v130
	v_fmac_f32_e32 v168, v160, v85
	v_max_f32_e32 v160, 0, v131
	v_fmac_f32_e32 v168, v161, v87
	v_fmac_f32_e32 v168, v160, v88
	v_max_f32_e32 v160, 0, v132
	v_max_f32_e32 v169, 0, v133
	v_fma_f32 v169, v169, v90, 0
	v_max_f32_e32 v161, 0, v134
	v_fmac_f32_e32 v169, v160, v89
	v_max_f32_e32 v160, 0, v135
	v_fmac_f32_e32 v169, v161, v91
	v_fmac_f32_e32 v169, v160, v92
	v_max_f32_e32 v160, 0, v136
	v_max_f32_e32 v170, 0, v137
	v_fma_f32 v170, v170, v94, 0
	v_max_f32_e32 v161, 0, v138
	v_fmac_f32_e32 v170, v160, v93
	v_max_f32_e32 v160, 0, v139
	v_fmac_f32_e32 v170, v161, v95
	v_fmac_f32_e32 v170, v160, v96
	v_max_f32_e32 v160, 0, v140
	v_max_f32_e32 v171, 0, v141
	v_fma_f32 v171, v171, v98, 0
	v_max_f32_e32 v161, 0, v142
	v_fmac_f32_e32 v171, v160, v97
	v_max_f32_e32 v160, 0, v143
	v_fmac_f32_e32 v171, v161, v99
	v_fmac_f32_e32 v171, v160, v100
	v_max_f32_e32 v160, 0, v144
	v_max_f32_e32 v172, 0, v145
	v_fma_f32 v172, v172, v102, 0
	v_max_f32_e32 v161, 0, v146
	v_fmac_f32_e32 v172, v160, v101
	v_max_f32_e32 v160, 0, v147
	v_fmac_f32_e32 v172, v161, v103
	v_fmac_f32_e32 v172, v160, v104
	v_max_f32_e32 v160, 0, v148
	v_max_f32_e32 v173, 0, v149
	v_fma_f32 v173, v173, v106, 0
	v_max_f32_e32 v161, 0, v150
	v_fmac_f32_e32 v173, v160, v105
	v_max_f32_e32 v160, 0, v151
	v_fmac_f32_e32 v173, v161, v107
	v_fmac_f32_e32 v173, v160, v108
	v_max_f32_e32 v160, 0, v152
	v_max_f32_e32 v174, 0, v153
	v_fma_f32 v174, v174, v110, 0
	v_max_f32_e32 v161, 0, v154
	v_fmac_f32_e32 v174, v160, v109
	v_max_f32_e32 v160, 0, v155
	v_fmac_f32_e32 v174, v161, v111
	v_fmac_f32_e32 v174, v160, v112
	v_max_f32_e32 v160, 0, v156
	v_max_f32_e32 v175, 0, v157
	v_fma_f32 v175, v175, v114, 0
	v_max_f32_e32 v161, 0, v158
	v_fmac_f32_e32 v175, v160, v113
	v_max_f32_e32 v160, 0, v159
	v_fmac_f32_e32 v175, v161, v115
	v_fmac_f32_e32 v175, v160, v116
	s_nop 0
	v_permlane16_swap_b32_e32 v168, v172
	v_permlane16_swap_b32_e32 v169, v173
	v_permlane16_swap_b32_e32 v170, v174
	v_permlane16_swap_b32_e32 v171, v175
	v_add_f32_e32 v168, v168, v172
	v_add_f32_e32 v169, v169, v173
	v_add_f32_e32 v170, v170, v174
	v_add_f32_e32 v171, v171, v175
	v_and_b32_e32 v160, 16, v252
	v_lshl_add_u32 v160, v160, 12, v119
	ds_write_b32 v160, v168
	ds_write_b32 v160, v169 offset:16384
	ds_write_b32 v160, v170 offset:32768
	ds_write_b32 v160, v171 offset:49152
	s_branch .LBB0_1084

; #define LAS __attribute__((address_space(3)))
; __device__ __forceinline__ unsigned pk2(float lo, float hi) { f32x2_t v = {lo, hi}; bf16x2_t b = __builtin_convertvector(v, bf16x2_t); return __builtin_bit_cast(unsigned, b); }
; __device__ __forceinline__ void dsa_unit32(const Args& a, LAS unsigned char* lds, const LAS unsigned long long* maskl, int b, int qb, int tid, int wave, int lane) {
;     ...
;     auto compute = [&](int buf, int kt) {
;         const unsigned long long mw = maskl[l31 * 32 + kt];
;         const LAS bf16* Ks = (const LAS bf16*)(lds + buf * STG); const LAS bf16* Vs = (const LAS bf16*)(lds + buf * STG + KBYTES);
;         f32x16 S2[2];
; #pragma unroll
;         for (int kh = 0; kh < 2; ++kh) {
; #pragma unroll
;             for (int i = 0; i < 16; ++i) S2[kh][i] = negB;
;             __builtin_amdgcn_s_setprio(1);
; #pragma unroll
;             for (int ks = 0; ks < 8; ++ks) S2[kh] = mfma32(*(const LAS bf16x8*)(Ks + (32 * kh + l31) * KS + 16 * ks + 8 * hi), qf[ks], S2[kh]);
;             __builtin_amdgcn_s_setprio(0);
;         }
; #pragma unroll
;         for (int kh = 0; kh < 2; ++kh) {
;             const unsigned mh = (unsigned)(mw >> (32 * kh + 4 * hi));
;             float p[16];
; #pragma unroll
;             for (int i = 0; i < 16; ++i) { const float e = __builtin_amdgcn_exp2f(S2[kh][i]);
;                 const int keep = __builtin_amdgcn_sbfe((int)mh, 8 * (i >> 2) + (i & 3), 1);
;                 p[i] = __builtin_bit_cast(float, __builtin_bit_cast(int, e) & keep); l += p[i]; }
;             u32x4 w0, w1;
;             w0.x = pk2(p[0], p[1]); w0.y = pk2(p[2], p[3]); w0.z = pk2(p[4], p[5]); w0.w = pk2(p[6], p[7]);
;             w1.x = pk2(p[8], p[9]); w1.y = pk2(p[10], p[11]); w1.z = pk2(p[12], p[13]); w1.w = pk2(p[14], p[15]);
;             const bf16x8 pa = __builtin_bit_cast(bf16x8, w0), pb = __builtin_bit_cast(bf16x8, w1);
;             __builtin_amdgcn_s_setprio(1);
; #pragma unroll
;             for (int ct = 0; ct < 4; ++ct) {
;                 const LAS bf16* vr = Vs + (32 * ct + l31) * VS + 4 * hi + 32 * kh;
;                 O[ct] = mfma32(cat8(*(const LAS u32x2*)(vr), *(const LAS u32x2*)(vr + 8)), pa, O[ct]);
;                 O[ct] = mfma32(cat8(*(const LAS u32x2*)(vr + 16), *(const LAS u32x2*)(vr + 24)), pb, O[ct]);
;             }
;             __builtin_amdgcn_s_setprio(0);
;         }
.LBB0_1304:
	s_cmp_lt_u32 s17, 4
	s_cbranch_scc0 .Ldsa_B0
	v_add_u32_e32 v207, -8, v206
	ds_read_b64 v[220:221], v207
	v_add_u32_e32 v207, v202, v180
	ds_read_b128 v[216:219], v207 offset:0
	ds_read_b128 v[228:231], v207 offset:32
	ds_read_b128 v[232:235], v207 offset:64
	ds_read_b128 v[236:239], v207 offset:96
	ds_read_b128 v[240:243], v207 offset:128
	ds_read_b128 v[244:247], v207 offset:160
	ds_read_b128 v[248:251], v207 offset:192
	ds_read_b128 v[222:225], v207 offset:224
	ds_read_b128 v[208:211], v207 offset:8704
	ds_read_b128 v[212:215], v207 offset:8736
	s_waitcnt lgkmcnt(9)
	v_mfma_f32_32x32x16_bf16 v[102:117], v[216:219], v[126:129], v[70:85]
	ds_read_b128 v[216:219], v207 offset:8768
	s_waitcnt lgkmcnt(9)
	v_mfma_f32_32x32x16_bf16 v[102:117], v[228:231], v[0:3], v[102:117]
	ds_read_b128 v[228:231], v207 offset:8800
	s_waitcnt lgkmcnt(9)
	v_mfma_f32_32x32x16_bf16 v[102:117], v[232:235], v[118:121], v[102:117]
	ds_read_b128 v[232:235], v207 offset:8832
	s_waitcnt lgkmcnt(9)
	v_mfma_f32_32x32x16_bf16 v[102:117], v[236:239], v[122:125], v[102:117]
	ds_read_b128 v[236:239], v207 offset:8864
	s_waitcnt lgkmcnt(9)
	v_mfma_f32_32x32x16_bf16 v[102:117], v[240:243], v[130:133], v[102:117]
	ds_read_b128 v[240:243], v207 offset:8896
	s_waitcnt lgkmcnt(9)
	v_mfma_f32_32x32x16_bf16 v[102:117], v[244:247], v[134:137], v[102:117]
	ds_read_b128 v[244:247], v207 offset:8928
	s_waitcnt lgkmcnt(9)
	v_mfma_f32_32x32x16_bf16 v[102:117], v[248:251], v[138:141], v[102:117]
	s_waitcnt lgkmcnt(8)
	v_mfma_f32_32x32x16_bf16 v[102:117], v[222:225], v[142:145], v[102:117]
	s_waitcnt lgkmcnt(7)
	v_mfma_f32_32x32x16_bf16 v[86:101], v[208:211], v[126:129], v[70:85]
	s_waitcnt lgkmcnt(6)
	v_mfma_f32_32x32x16_bf16 v[86:101], v[212:215], v[0:3], v[86:101]
	s_waitcnt lgkmcnt(5)
	v_mfma_f32_32x32x16_bf16 v[86:101], v[216:219], v[118:121], v[86:101]
	ds_read_b128 v[248:251], v203 offset:17408
	ds_read_b128 v[222:225], v203 offset:17440
	ds_read_b128 v[216:219], v203 offset:22016
	s_waitcnt lgkmcnt(7)
	v_mfma_f32_32x32x16_bf16 v[86:101], v[228:231], v[122:125], v[86:101]
	ds_read_b128 v[228:231], v203 offset:22048
	s_waitcnt lgkmcnt(7)
	v_mfma_f32_32x32x16_bf16 v[86:101], v[232:235], v[130:133], v[86:101]
	ds_read_b128 v[232:235], v203 offset:26624
	s_waitcnt lgkmcnt(7)
	v_mfma_f32_32x32x16_bf16 v[86:101], v[236:239], v[134:137], v[86:101]
	ds_read_b128 v[236:239], v203 offset:26656
	s_waitcnt lgkmcnt(7)
	v_mfma_f32_32x32x16_bf16 v[86:101], v[240:243], v[138:141], v[86:101]
	ds_read_b128 v[240:243], v203 offset:31232
	s_waitcnt lgkmcnt(7)
	v_mfma_f32_32x32x16_bf16 v[86:101], v[244:247], v[142:145], v[86:101]
	ds_read_b128 v[244:247], v203 offset:31264
	v_lshrrev_b64 v[208:209], v182, v[220:221]
	v_exp_f32_e32 v102, v102
	v_bfe_i32 v209, v208, 0, 1
	v_exp_f32_e32 v103, v103
	v_bfe_i32 v210, v208, 1, 1
	v_and_b32_e32 v102, v102, v209
	v_exp_f32_e32 v104, v104
	v_bfe_i32 v211, v208, 2, 1
	v_and_b32_e32 v103, v103, v210
	v_exp_f32_e32 v105, v105
	v_bfe_i32 v209, v208, 3, 1
	v_and_b32_e32 v104, v104, v211
	v_exp_f32_e32 v106, v106
	v_bfe_i32 v210, v208, 8, 1
	v_and_b32_e32 v105, v105, v209
	v_exp_f32_e32 v107, v107
	v_bfe_i32 v211, v208, 9, 1
	v_and_b32_e32 v106, v106, v210
	v_exp_f32_e32 v108, v108
	v_bfe_i32 v209, v208, 10, 1
	v_and_b32_e32 v107, v107, v211
	v_exp_f32_e32 v109, v109
	v_bfe_i32 v210, v208, 11, 1
	v_and_b32_e32 v108, v108, v209
	v_exp_f32_e32 v110, v110
	v_bfe_i32 v211, v208, 16, 1
	v_and_b32_e32 v109, v109, v210
	v_exp_f32_e32 v111, v111
	v_bfe_i32 v209, v208, 17, 1
	v_and_b32_e32 v110, v110, v211
	v_exp_f32_e32 v112, v112
	v_bfe_i32 v210, v208, 18, 1
	v_and_b32_e32 v111, v111, v209
	v_exp_f32_e32 v113, v113
	v_bfe_i32 v211, v208, 19, 1
	v_and_b32_e32 v112, v112, v210
	v_exp_f32_e32 v114, v114
	v_bfe_i32 v209, v208, 24, 1
	v_and_b32_e32 v113, v113, v211
	v_exp_f32_e32 v115, v115
	v_bfe_i32 v210, v208, 25, 1
	v_and_b32_e32 v114, v114, v209
	v_exp_f32_e32 v116, v116
	v_bfe_i32 v211, v208, 26, 1
	v_and_b32_e32 v115, v115, v210
	v_exp_f32_e32 v117, v117
	v_bfe_i32 v209, v208, 27, 1
	v_and_b32_e32 v116, v116, v211
	s_nop 0
	v_and_b32_e32 v117, v117, v209
	v_cvt_pk_bf16_f32 v208, v102, v103
	v_cvt_pk_bf16_f32 v209, v104, v105
	v_cvt_pk_bf16_f32 v210, v106, v107
	v_cvt_pk_bf16_f32 v211, v108, v109
	v_cvt_pk_bf16_f32 v212, v110, v111
	v_cvt_pk_bf16_f32 v213, v112, v113
	v_cvt_pk_bf16_f32 v214, v114, v115
	v_cvt_pk_bf16_f32 v215, v116, v117
	s_nop 1
	s_waitcnt lgkmcnt(7)
	v_mfma_f32_32x32x16_bf16 v[54:69], v[248:251], v[208:211], v[54:69]
	ds_read_b128 v[248:251], v203 offset:17472
	v_add_f32_e32 v194, v194, v102
	v_add_f32_e32 v194, v103, v194
	s_waitcnt lgkmcnt(7)
	v_mfma_f32_32x32x16_bf16 v[54:69], v[222:225], v[212:215], v[54:69]
	ds_read_b128 v[222:225], v203 offset:17504
	v_add_f32_e32 v194, v104, v194
	v_add_f32_e32 v194, v105, v194
	s_waitcnt lgkmcnt(7)
	v_mfma_f32_32x32x16_bf16 v[38:53], v[216:219], v[208:211], v[38:53]
	ds_read_b128 v[216:219], v203 offset:22080
	v_add_f32_e32 v194, v106, v194
	v_add_f32_e32 v194, v107, v194
	s_waitcnt lgkmcnt(7)
	v_mfma_f32_32x32x16_bf16 v[38:53], v[228:231], v[212:215], v[38:53]
	ds_read_b128 v[228:231], v203 offset:22112
	v_add_f32_e32 v194, v108, v194
	v_add_f32_e32 v194, v109, v194
	s_waitcnt lgkmcnt(7)
	v_mfma_f32_32x32x16_bf16 v[22:37], v[232:235], v[208:211], v[22:37]
	ds_read_b128 v[232:235], v203 offset:26688
	v_add_f32_e32 v194, v110, v194
	v_add_f32_e32 v194, v111, v194
	s_waitcnt lgkmcnt(7)
	v_mfma_f32_32x32x16_bf16 v[22:37], v[236:239], v[212:215], v[22:37]
	ds_read_b128 v[236:239], v203 offset:26720
	v_add_f32_e32 v194, v112, v194
	v_add_f32_e32 v194, v113, v194
	s_waitcnt lgkmcnt(7)
; #define LAS __attribute__((address_space(3)))
; __device__ __forceinline__ unsigned pk2(float lo, float hi) { f32x2_t v = {lo, hi}; bf16x2_t b = __builtin_convertvector(v, bf16x2_t); return __builtin_bit_cast(unsigned, b); }
; __device__ __forceinline__ void dsa_unit32(const Args& a, LAS unsigned char* lds, const LAS unsigned long long* maskl, int b, int qb, int tid, int wave, int lane) {
;     ...
;     auto compute = [&](int buf, int kt) {
;         const unsigned long long mw = maskl[l31 * 32 + kt];
;         const LAS bf16* Ks = (const LAS bf16*)(lds + buf * STG); const LAS bf16* Vs = (const LAS bf16*)(lds + buf * STG + KBYTES);
;         f32x16 S2[2];
; #pragma unroll
;         for (int kh = 0; kh < 2; ++kh) {
; #pragma unroll
;             for (int i = 0; i < 16; ++i) S2[kh][i] = negB;
;             __builtin_amdgcn_s_setprio(1);
; #pragma unroll
;             for (int ks = 0; ks < 8; ++ks) S2[kh] = mfma32(*(const LAS bf16x8*)(Ks + (32 * kh + l31) * KS + 16 * ks + 8 * hi), qf[ks], S2[kh]);
;             __builtin_amdgcn_s_setprio(0);
;         }
; #pragma unroll
;         for (int kh = 0; kh < 2; ++kh) {
;             const unsigned mh = (unsigned)(mw >> (32 * kh + 4 * hi));
;             float p[16];
; #pragma unroll
;             for (int i = 0; i < 16; ++i) { const float e = __builtin_amdgcn_exp2f(S2[kh][i]);
;                 const int keep = __builtin_amdgcn_sbfe((int)mh, 8 * (i >> 2) + (i & 3), 1);
;                 p[i] = __builtin_bit_cast(float, __builtin_bit_cast(int, e) & keep); l += p[i]; }
;             u32x4 w0, w1;
;             w0.x = pk2(p[0], p[1]); w0.y = pk2(p[2], p[3]); w0.z = pk2(p[4], p[5]); w0.w = pk2(p[6], p[7]);
;             w1.x = pk2(p[8], p[9]); w1.y = pk2(p[10], p[11]); w1.z = pk2(p[12], p[13]); w1.w = pk2(p[14], p[15]);
;             const bf16x8 pa = __builtin_bit_cast(bf16x8, w0), pb = __builtin_bit_cast(bf16x8, w1);
;             __builtin_amdgcn_s_setprio(1);
; #pragma unroll
;             for (int ct = 0; ct < 4; ++ct) {
;                 const LAS bf16* vr = Vs + (32 * ct + l31) * VS + 4 * hi + 32 * kh;
;                 O[ct] = mfma32(cat8(*(const LAS u32x2*)(vr), *(const LAS u32x2*)(vr + 8)), pa, O[ct]);
;                 O[ct] = mfma32(cat8(*(const LAS u32x2*)(vr + 16), *(const LAS u32x2*)(vr + 24)), pb, O[ct]);
;             }
;             __builtin_amdgcn_s_setprio(0);
;         }
	v_mfma_f32_32x32x16_bf16 v[6:21], v[240:243], v[208:211], v[6:21]
	ds_read_b128 v[240:243], v203 offset:31296
	v_add_f32_e32 v194, v114, v194
	v_add_f32_e32 v194, v115, v194
	s_waitcnt lgkmcnt(7)
	v_mfma_f32_32x32x16_bf16 v[6:21], v[244:247], v[212:215], v[6:21]
	ds_read_b128 v[244:247], v203 offset:31328
	v_add_f32_e32 v194, v116, v194
	v_add_f32_e32 v194, v117, v194
	v_lshrrev_b64 v[208:209], v184, v[220:221]
	v_exp_f32_e32 v86, v86
	v_bfe_i32 v209, v208, 0, 1
	v_exp_f32_e32 v87, v87
	v_bfe_i32 v210, v208, 1, 1
	v_and_b32_e32 v86, v86, v209
	v_exp_f32_e32 v88, v88
	v_bfe_i32 v211, v208, 2, 1
	v_and_b32_e32 v87, v87, v210
	v_exp_f32_e32 v89, v89
	v_bfe_i32 v209, v208, 3, 1
	v_and_b32_e32 v88, v88, v211
	v_exp_f32_e32 v90, v90
	v_bfe_i32 v210, v208, 8, 1
	v_and_b32_e32 v89, v89, v209
	v_exp_f32_e32 v91, v91
	v_bfe_i32 v211, v208, 9, 1
	v_and_b32_e32 v90, v90, v210
	v_exp_f32_e32 v92, v92
	v_bfe_i32 v209, v208, 10, 1
	v_and_b32_e32 v91, v91, v211
	v_exp_f32_e32 v93, v93
	v_bfe_i32 v210, v208, 11, 1
	v_and_b32_e32 v92, v92, v209
	v_exp_f32_e32 v94, v94
	v_bfe_i32 v211, v208, 16, 1
	v_and_b32_e32 v93, v93, v210
	v_exp_f32_e32 v95, v95
	v_bfe_i32 v209, v208, 17, 1
	v_and_b32_e32 v94, v94, v211
	v_exp_f32_e32 v96, v96
	v_bfe_i32 v210, v208, 18, 1
	v_and_b32_e32 v95, v95, v209
	v_exp_f32_e32 v97, v97
	v_bfe_i32 v211, v208, 19, 1
	v_and_b32_e32 v96, v96, v210
	v_exp_f32_e32 v98, v98
	v_bfe_i32 v209, v208, 24, 1
	v_and_b32_e32 v97, v97, v211
	v_exp_f32_e32 v99, v99
	v_bfe_i32 v210, v208, 25, 1
	v_and_b32_e32 v98, v98, v209
	v_exp_f32_e32 v100, v100
	v_bfe_i32 v211, v208, 26, 1
	v_and_b32_e32 v99, v99, v210
	v_exp_f32_e32 v101, v101
	v_bfe_i32 v209, v208, 27, 1
	v_and_b32_e32 v100, v100, v211
	s_nop 0
	v_and_b32_e32 v101, v101, v209
	v_cvt_pk_bf16_f32 v208, v86, v87
	v_cvt_pk_bf16_f32 v209, v88, v89
	v_cvt_pk_bf16_f32 v210, v90, v91
	v_cvt_pk_bf16_f32 v211, v92, v93
	v_cvt_pk_bf16_f32 v212, v94, v95
	v_cvt_pk_bf16_f32 v213, v96, v97
	v_cvt_pk_bf16_f32 v214, v98, v99
	v_cvt_pk_bf16_f32 v215, v100, v101
	s_nop 1
	s_waitcnt lgkmcnt(7)
	v_mfma_f32_32x32x16_bf16 v[54:69], v[248:251], v[208:211], v[54:69]
	v_add_f32_e32 v194, v194, v86
	v_add_f32_e32 v194, v87, v194
	s_waitcnt lgkmcnt(6)
	v_mfma_f32_32x32x16_bf16 v[54:69], v[222:225], v[212:215], v[54:69]
	v_add_f32_e32 v194, v88, v194
	v_add_f32_e32 v194, v89, v194
	s_waitcnt lgkmcnt(5)
	v_mfma_f32_32x32x16_bf16 v[38:53], v[216:219], v[208:211], v[38:53]
	v_add_f32_e32 v194, v90, v194
	v_add_f32_e32 v194, v91, v194
	s_waitcnt lgkmcnt(4)
	v_mfma_f32_32x32x16_bf16 v[38:53], v[228:231], v[212:215], v[38:53]
	v_add_f32_e32 v194, v92, v194
	v_add_f32_e32 v194, v93, v194
	s_waitcnt lgkmcnt(3)
	v_mfma_f32_32x32x16_bf16 v[22:37], v[232:235], v[208:211], v[22:37]
	v_add_f32_e32 v194, v94, v194
	v_add_f32_e32 v194, v95, v194
	s_waitcnt lgkmcnt(2)
	v_mfma_f32_32x32x16_bf16 v[22:37], v[236:239], v[212:215], v[22:37]
	v_add_f32_e32 v194, v96, v194
	v_add_f32_e32 v194, v97, v194
	s_waitcnt lgkmcnt(1)
	v_mfma_f32_32x32x16_bf16 v[6:21], v[240:243], v[208:211], v[6:21]
	v_add_f32_e32 v194, v98, v194
	v_add_f32_e32 v194, v99, v194
	s_waitcnt lgkmcnt(0)
	v_mfma_f32_32x32x16_bf16 v[6:21], v[244:247], v[212:215], v[6:21]
	v_add_f32_e32 v194, v100, v194
	v_add_f32_e32 v194, v101, v194
	s_branch .Ldsa_J0
.Ldsa_B0:
	v_add_u32_e32 v207, -8, v206
	ds_read_b64 v[220:221], v207
	v_add_u32_e32 v207, v202, v180
	ds_read_b128 v[216:219], v207 offset:0
	ds_read_b128 v[228:231], v207 offset:32
	ds_read_b128 v[232:235], v207 offset:64
	ds_read_b128 v[236:239], v207 offset:96
	ds_read_b128 v[240:243], v207 offset:128
	ds_read_b128 v[244:247], v207 offset:160
	ds_read_b128 v[248:251], v207 offset:192
	ds_read_b128 v[222:225], v207 offset:224
	s_waitcnt lgkmcnt(7)
	v_mfma_f32_32x32x16_bf16 v[102:117], v[216:219], v[126:129], v[70:85]
	ds_read_b128 v[216:219], v207 offset:8704
	s_waitcnt lgkmcnt(7)
	v_mfma_f32_32x32x16_bf16 v[102:117], v[228:231], v[0:3], v[102:117]
	ds_read_b128 v[228:231], v207 offset:8736
	s_waitcnt lgkmcnt(7)
	v_mfma_f32_32x32x16_bf16 v[102:117], v[232:235], v[118:121], v[102:117]
	ds_read_b128 v[232:235], v207 offset:8768
	s_waitcnt lgkmcnt(7)
	v_mfma_f32_32x32x16_bf16 v[102:117], v[236:239], v[122:125], v[102:117]
	ds_read_b128 v[236:239], v207 offset:8800
	s_waitcnt lgkmcnt(7)
	v_mfma_f32_32x32x16_bf16 v[102:117], v[240:243], v[130:133], v[102:117]
	ds_read_b128 v[240:243], v207 offset:8832
	s_waitcnt lgkmcnt(7)
	v_mfma_f32_32x32x16_bf16 v[102:117], v[244:247], v[134:137], v[102:117]
	ds_read_b128 v[244:247], v207 offset:8864
	s_waitcnt lgkmcnt(7)
	v_mfma_f32_32x32x16_bf16 v[102:117], v[248:251], v[138:141], v[102:117]
	ds_read_b128 v[248:251], v207 offset:8896
	s_waitcnt lgkmcnt(7)
	v_mfma_f32_32x32x16_bf16 v[102:117], v[222:225], v[142:145], v[102:117]
	ds_read_b128 v[222:225], v207 offset:8928
	s_nop 7
	s_nop 3
	v_lshrrev_b64 v[208:209], v182, v[220:221]
	v_exp_f32_e32 v102, v102
	v_bfe_i32 v209, v208, 0, 1
	v_exp_f32_e32 v103, v103
	v_bfe_i32 v210, v208, 1, 1
	v_and_b32_e32 v102, v102, v209
	v_exp_f32_e32 v104, v104
	v_bfe_i32 v211, v208, 2, 1
	v_and_b32_e32 v103, v103, v210
	v_exp_f32_e32 v105, v105
	v_bfe_i32 v209, v208, 3, 1
	v_and_b32_e32 v104, v104, v211
	v_exp_f32_e32 v106, v106
	v_bfe_i32 v210, v208, 8, 1
	v_and_b32_e32 v105, v105, v209
	v_exp_f32_e32 v107, v107
	v_bfe_i32 v211, v208, 9, 1
	v_and_b32_e32 v106, v106, v210
	v_exp_f32_e32 v108, v108
	v_bfe_i32 v209, v208, 10, 1
	v_and_b32_e32 v107, v107, v211
	v_exp_f32_e32 v109, v109
	v_bfe_i32 v210, v208, 11, 1
	v_and_b32_e32 v108, v108, v209
	v_exp_f32_e32 v110, v110
	v_bfe_i32 v211, v208, 16, 1
	v_and_b32_e32 v109, v109, v210
	v_exp_f32_e32 v111, v111
	v_bfe_i32 v209, v208, 17, 1
	v_and_b32_e32 v110, v110, v211
	v_exp_f32_e32 v112, v112
	v_bfe_i32 v210, v208, 18, 1
	v_and_b32_e32 v111, v111, v209
	v_exp_f32_e32 v113, v113
	v_bfe_i32 v211, v208, 19, 1
	v_and_b32_e32 v112, v112, v210
	v_exp_f32_e32 v114, v114
	v_bfe_i32 v209, v208, 24, 1
	v_and_b32_e32 v113, v113, v211
	v_exp_f32_e32 v115, v115
	v_bfe_i32 v210, v208, 25, 1
	v_and_b32_e32 v114, v114, v209
	v_exp_f32_e32 v116, v116
	v_bfe_i32 v211, v208, 26, 1
	v_and_b32_e32 v115, v115, v210
	v_exp_f32_e32 v117, v117
	v_bfe_i32 v209, v208, 27, 1
	v_and_b32_e32 v116, v116, v211
	s_nop 0
	v_and_b32_e32 v117, v117, v209
	v_cvt_pk_bf16_f32 v208, v102, v103
	v_cvt_pk_bf16_f32 v209, v104, v105
	v_cvt_pk_bf16_f32 v210, v106, v107
	v_cvt_pk_bf16_f32 v211, v108, v109
	v_cvt_pk_bf16_f32 v212, v110, v111
	v_cvt_pk_bf16_f32 v213, v112, v113
	v_cvt_pk_bf16_f32 v214, v114, v115
	v_cvt_pk_bf16_f32 v215, v116, v117
	s_waitcnt lgkmcnt(7)
; #define LAS __attribute__((address_space(3)))
; __device__ __forceinline__ unsigned pk2(float lo, float hi) { f32x2_t v = {lo, hi}; bf16x2_t b = __builtin_convertvector(v, bf16x2_t); return __builtin_bit_cast(unsigned, b); }
; __device__ __forceinline__ void dsa_unit32(const Args& a, LAS unsigned char* lds, const LAS unsigned long long* maskl, int b, int qb, int tid, int wave, int lane) {
;     ...
;     auto compute = [&](int buf, int kt) {
;         const unsigned long long mw = maskl[l31 * 32 + kt];
;         const LAS bf16* Ks = (const LAS bf16*)(lds + buf * STG); const LAS bf16* Vs = (const LAS bf16*)(lds + buf * STG + KBYTES);
;         f32x16 S2[2];
; #pragma unroll
;         for (int kh = 0; kh < 2; ++kh) {
; #pragma unroll
;             for (int i = 0; i < 16; ++i) S2[kh][i] = negB;
;             __builtin_amdgcn_s_setprio(1);
; #pragma unroll
;             for (int ks = 0; ks < 8; ++ks) S2[kh] = mfma32(*(const LAS bf16x8*)(Ks + (32 * kh + l31) * KS + 16 * ks + 8 * hi), qf[ks], S2[kh]);
;             __builtin_amdgcn_s_setprio(0);
;         }
; #pragma unroll
;         for (int kh = 0; kh < 2; ++kh) {
;             const unsigned mh = (unsigned)(mw >> (32 * kh + 4 * hi));
;             float p[16];
; #pragma unroll
;             for (int i = 0; i < 16; ++i) { const float e = __builtin_amdgcn_exp2f(S2[kh][i]);
;                 const int keep = __builtin_amdgcn_sbfe((int)mh, 8 * (i >> 2) + (i & 3), 1);
;                 p[i] = __builtin_bit_cast(float, __builtin_bit_cast(int, e) & keep); l += p[i]; }
;             u32x4 w0, w1;
;             w0.x = pk2(p[0], p[1]); w0.y = pk2(p[2], p[3]); w0.z = pk2(p[4], p[5]); w0.w = pk2(p[6], p[7]);
;             w1.x = pk2(p[8], p[9]); w1.y = pk2(p[10], p[11]); w1.z = pk2(p[12], p[13]); w1.w = pk2(p[14], p[15]);
;             const bf16x8 pa = __builtin_bit_cast(bf16x8, w0), pb = __builtin_bit_cast(bf16x8, w1);
;             __builtin_amdgcn_s_setprio(1);
; #pragma unroll
;             for (int ct = 0; ct < 4; ++ct) {
;                 const LAS bf16* vr = Vs + (32 * ct + l31) * VS + 4 * hi + 32 * kh;
;                 O[ct] = mfma32(cat8(*(const LAS u32x2*)(vr), *(const LAS u32x2*)(vr + 8)), pa, O[ct]);
;                 O[ct] = mfma32(cat8(*(const LAS u32x2*)(vr + 16), *(const LAS u32x2*)(vr + 24)), pb, O[ct]);
;             }
;             __builtin_amdgcn_s_setprio(0);
;         }
	v_mfma_f32_32x32x16_bf16 v[86:101], v[216:219], v[126:129], v[70:85]
	ds_read_b128 v[216:219], v203 offset:17408
	s_waitcnt lgkmcnt(7)
	v_mfma_f32_32x32x16_bf16 v[86:101], v[228:231], v[0:3], v[86:101]
	ds_read_b128 v[228:231], v203 offset:17440
	s_waitcnt lgkmcnt(7)
	v_mfma_f32_32x32x16_bf16 v[86:101], v[232:235], v[118:121], v[86:101]
	ds_read_b128 v[232:235], v203 offset:22016
	s_waitcnt lgkmcnt(7)
	v_mfma_f32_32x32x16_bf16 v[86:101], v[236:239], v[122:125], v[86:101]
	ds_read_b128 v[236:239], v203 offset:22048
	s_waitcnt lgkmcnt(7)
	v_mfma_f32_32x32x16_bf16 v[86:101], v[240:243], v[130:133], v[86:101]
	ds_read_b128 v[240:243], v203 offset:26624
	s_waitcnt lgkmcnt(7)
	v_mfma_f32_32x32x16_bf16 v[86:101], v[244:247], v[134:137], v[86:101]
	ds_read_b128 v[244:247], v203 offset:26656
	s_waitcnt lgkmcnt(7)
	v_mfma_f32_32x32x16_bf16 v[86:101], v[248:251], v[138:141], v[86:101]
	ds_read_b128 v[248:251], v203 offset:31232
	s_waitcnt lgkmcnt(7)
	v_mfma_f32_32x32x16_bf16 v[86:101], v[222:225], v[142:145], v[86:101]
	ds_read_b128 v[222:225], v203 offset:31264
	v_add_f32_e32 v194, v194, v102
	v_add_f32_e32 v194, v103, v194
	v_add_f32_e32 v194, v104, v194
	v_add_f32_e32 v194, v105, v194
	v_add_f32_e32 v194, v106, v194
	v_add_f32_e32 v194, v107, v194
	v_add_f32_e32 v194, v108, v194
	v_add_f32_e32 v194, v109, v194
	v_add_f32_e32 v194, v110, v194
	v_add_f32_e32 v194, v111, v194
	v_add_f32_e32 v194, v112, v194
	v_add_f32_e32 v194, v113, v194
	v_add_f32_e32 v194, v114, v194
	v_add_f32_e32 v194, v115, v194
	v_add_f32_e32 v194, v116, v194
	v_add_f32_e32 v194, v117, v194
	v_lshrrev_b64 v[110:111], v184, v[220:221]
	v_exp_f32_e32 v86, v86
	v_bfe_i32 v111, v110, 0, 1
	v_exp_f32_e32 v87, v87
	v_bfe_i32 v112, v110, 1, 1
	v_and_b32_e32 v86, v86, v111
	v_exp_f32_e32 v88, v88
	v_bfe_i32 v113, v110, 2, 1
	v_and_b32_e32 v87, v87, v112
	v_exp_f32_e32 v89, v89
	v_bfe_i32 v111, v110, 3, 1
	v_and_b32_e32 v88, v88, v113
	v_exp_f32_e32 v90, v90
	v_bfe_i32 v112, v110, 8, 1
	v_and_b32_e32 v89, v89, v111
	v_exp_f32_e32 v91, v91
	v_bfe_i32 v113, v110, 9, 1
	v_and_b32_e32 v90, v90, v112
	v_exp_f32_e32 v92, v92
	v_bfe_i32 v111, v110, 10, 1
	v_and_b32_e32 v91, v91, v113
	v_exp_f32_e32 v93, v93
	v_bfe_i32 v112, v110, 11, 1
	v_and_b32_e32 v92, v92, v111
	v_exp_f32_e32 v94, v94
	v_bfe_i32 v113, v110, 16, 1
	v_and_b32_e32 v93, v93, v112
	v_exp_f32_e32 v95, v95
	v_bfe_i32 v111, v110, 17, 1
	v_and_b32_e32 v94, v94, v113
	v_exp_f32_e32 v96, v96
	v_bfe_i32 v112, v110, 18, 1
	v_and_b32_e32 v95, v95, v111
	v_exp_f32_e32 v97, v97
	v_bfe_i32 v113, v110, 19, 1
	v_and_b32_e32 v96, v96, v112
	v_exp_f32_e32 v98, v98
	v_bfe_i32 v111, v110, 24, 1
	v_and_b32_e32 v97, v97, v113
	v_exp_f32_e32 v99, v99
	v_bfe_i32 v112, v110, 25, 1
	v_and_b32_e32 v98, v98, v111
	v_exp_f32_e32 v100, v100
	v_bfe_i32 v113, v110, 26, 1
	v_and_b32_e32 v99, v99, v112
	v_exp_f32_e32 v101, v101
	v_bfe_i32 v111, v110, 27, 1
	v_and_b32_e32 v100, v100, v113
	s_nop 0
	v_and_b32_e32 v101, v101, v111
	v_cvt_pk_bf16_f32 v102, v86, v87
	v_cvt_pk_bf16_f32 v103, v88, v89
	v_cvt_pk_bf16_f32 v104, v90, v91
	v_cvt_pk_bf16_f32 v105, v92, v93
	v_cvt_pk_bf16_f32 v106, v94, v95
	v_cvt_pk_bf16_f32 v107, v96, v97
	v_cvt_pk_bf16_f32 v108, v98, v99
	v_cvt_pk_bf16_f32 v109, v100, v101
	s_nop 1
	s_waitcnt lgkmcnt(7)
	v_mfma_f32_32x32x16_bf16 v[54:69], v[216:219], v[208:211], v[54:69]
	ds_read_b128 v[216:219], v203 offset:17472
	s_waitcnt lgkmcnt(7)
	v_mfma_f32_32x32x16_bf16 v[54:69], v[228:231], v[212:215], v[54:69]
	ds_read_b128 v[228:231], v203 offset:17504
	s_waitcnt lgkmcnt(7)
	v_mfma_f32_32x32x16_bf16 v[38:53], v[232:235], v[208:211], v[38:53]
	ds_read_b128 v[232:235], v203 offset:22080
	s_waitcnt lgkmcnt(7)
	v_mfma_f32_32x32x16_bf16 v[38:53], v[236:239], v[212:215], v[38:53]
	ds_read_b128 v[236:239], v203 offset:22112
	s_waitcnt lgkmcnt(7)
	v_mfma_f32_32x32x16_bf16 v[22:37], v[240:243], v[208:211], v[22:37]
	ds_read_b128 v[240:243], v203 offset:26688
	s_waitcnt lgkmcnt(7)
	v_mfma_f32_32x32x16_bf16 v[22:37], v[244:247], v[212:215], v[22:37]
	ds_read_b128 v[244:247], v203 offset:26720
	s_waitcnt lgkmcnt(7)
	v_mfma_f32_32x32x16_bf16 v[6:21], v[248:251], v[208:211], v[6:21]
	ds_read_b128 v[248:251], v203 offset:31296
	s_waitcnt lgkmcnt(7)
	v_mfma_f32_32x32x16_bf16 v[6:21], v[222:225], v[212:215], v[6:21]
	ds_read_b128 v[222:225], v203 offset:31328
	s_waitcnt lgkmcnt(7)
	v_mfma_f32_32x32x16_bf16 v[54:69], v[216:219], v[102:105], v[54:69]
	v_add_f32_e32 v194, v194, v86
	v_add_f32_e32 v194, v87, v194
	s_waitcnt lgkmcnt(6)
	v_mfma_f32_32x32x16_bf16 v[54:69], v[228:231], v[106:109], v[54:69]
	v_add_f32_e32 v194, v88, v194
	v_add_f32_e32 v194, v89, v194
	s_waitcnt lgkmcnt(5)
	v_mfma_f32_32x32x16_bf16 v[38:53], v[232:235], v[102:105], v[38:53]
	v_add_f32_e32 v194, v90, v194
	v_add_f32_e32 v194, v91, v194
	s_waitcnt lgkmcnt(4)
	v_mfma_f32_32x32x16_bf16 v[38:53], v[236:239], v[106:109], v[38:53]
	v_add_f32_e32 v194, v92, v194
	v_add_f32_e32 v194, v93, v194
	s_waitcnt lgkmcnt(3)
	v_mfma_f32_32x32x16_bf16 v[22:37], v[240:243], v[102:105], v[22:37]
	v_add_f32_e32 v194, v94, v194
	v_add_f32_e32 v194, v95, v194
	s_waitcnt lgkmcnt(2)
	v_mfma_f32_32x32x16_bf16 v[22:37], v[244:247], v[106:109], v[22:37]
	v_add_f32_e32 v194, v96, v194
	v_add_f32_e32 v194, v97, v194
	s_waitcnt lgkmcnt(1)
	v_mfma_f32_32x32x16_bf16 v[6:21], v[248:251], v[102:105], v[6:21]
	v_add_f32_e32 v194, v98, v194
	v_add_f32_e32 v194, v99, v194
	s_waitcnt lgkmcnt(0)
	v_mfma_f32_32x32x16_bf16 v[6:21], v[222:225], v[106:109], v[6:21]
	v_add_f32_e32 v194, v100, v194
	v_add_f32_e32 v194, v101, v194

; #define LAS __attribute__((address_space(3)))
; __device__ __forceinline__ unsigned pk2(float lo, float hi) { f32x2_t v = {lo, hi}; bf16x2_t b = __builtin_convertvector(v, bf16x2_t); return __builtin_bit_cast(unsigned, b); }
; __device__ __forceinline__ void dsa_unit32(const Args& a, LAS unsigned char* lds, const LAS unsigned long long* maskl, int b, int qb, int tid, int wave, int lane) {
;     ...
;     auto compute = [&](int buf, int kt) {
;         const unsigned long long mw = maskl[l31 * 32 + kt];
;         const LAS bf16* Ks = (const LAS bf16*)(lds + buf * STG); const LAS bf16* Vs = (const LAS bf16*)(lds + buf * STG + KBYTES);
;         f32x16 S2[2];
; #pragma unroll
;         for (int kh = 0; kh < 2; ++kh) {
; #pragma unroll
;             for (int i = 0; i < 16; ++i) S2[kh][i] = negB;
;             __builtin_amdgcn_s_setprio(1);
; #pragma unroll
;             for (int ks = 0; ks < 8; ++ks) S2[kh] = mfma32(*(const LAS bf16x8*)(Ks + (32 * kh + l31) * KS + 16 * ks + 8 * hi), qf[ks], S2[kh]);
;             __builtin_amdgcn_s_setprio(0);
;         }
; #pragma unroll
;         for (int kh = 0; kh < 2; ++kh) {
;             const unsigned mh = (unsigned)(mw >> (32 * kh + 4 * hi));
;             float p[16];
; #pragma unroll
;             for (int i = 0; i < 16; ++i) { const float e = __builtin_amdgcn_exp2f(S2[kh][i]);
;                 const int keep = __builtin_amdgcn_sbfe((int)mh, 8 * (i >> 2) + (i & 3), 1);
;                 p[i] = __builtin_bit_cast(float, __builtin_bit_cast(int, e) & keep); l += p[i]; }
;             u32x4 w0, w1;
;             w0.x = pk2(p[0], p[1]); w0.y = pk2(p[2], p[3]); w0.z = pk2(p[4], p[5]); w0.w = pk2(p[6], p[7]);
;             w1.x = pk2(p[8], p[9]); w1.y = pk2(p[10], p[11]); w1.z = pk2(p[12], p[13]); w1.w = pk2(p[14], p[15]);
;             const bf16x8 pa = __builtin_bit_cast(bf16x8, w0), pb = __builtin_bit_cast(bf16x8, w1);
;             __builtin_amdgcn_s_setprio(1);
; #pragma unroll
;             for (int ct = 0; ct < 4; ++ct) {
;                 const LAS bf16* vr = Vs + (32 * ct + l31) * VS + 4 * hi + 32 * kh;
;                 O[ct] = mfma32(cat8(*(const LAS u32x2*)(vr), *(const LAS u32x2*)(vr + 8)), pa, O[ct]);
;                 O[ct] = mfma32(cat8(*(const LAS u32x2*)(vr + 16), *(const LAS u32x2*)(vr + 24)), pb, O[ct]);
;             }
;             __builtin_amdgcn_s_setprio(0);
;         }
.LBB0_1309:
	s_cmp_lt_u32 s17, 4
	s_cbranch_scc0 .Ldsa_B1
	ds_read_b64 v[220:221], v206
	v_add_u32_e32 v207, v202, v180
	ds_read_b128 v[216:219], v207 offset:36864
	ds_read_b128 v[228:231], v207 offset:36896
	ds_read_b128 v[232:235], v207 offset:36928
	ds_read_b128 v[236:239], v207 offset:36960
	ds_read_b128 v[240:243], v207 offset:36992
	ds_read_b128 v[244:247], v207 offset:37024
	ds_read_b128 v[248:251], v207 offset:37056
	ds_read_b128 v[222:225], v207 offset:37088
	ds_read_b128 v[208:211], v207 offset:45568
	ds_read_b128 v[212:215], v207 offset:45600
	s_waitcnt lgkmcnt(9)
	v_mfma_f32_32x32x16_bf16 v[102:117], v[216:219], v[126:129], v[70:85]
	ds_read_b128 v[216:219], v207 offset:45632
	s_waitcnt lgkmcnt(9)
	v_mfma_f32_32x32x16_bf16 v[102:117], v[228:231], v[0:3], v[102:117]
	ds_read_b128 v[228:231], v207 offset:45664
	s_waitcnt lgkmcnt(9)
	v_mfma_f32_32x32x16_bf16 v[102:117], v[232:235], v[118:121], v[102:117]
	ds_read_b128 v[232:235], v207 offset:45696
	s_waitcnt lgkmcnt(9)
	v_mfma_f32_32x32x16_bf16 v[102:117], v[236:239], v[122:125], v[102:117]
	ds_read_b128 v[236:239], v207 offset:45728
	s_waitcnt lgkmcnt(9)
	v_mfma_f32_32x32x16_bf16 v[102:117], v[240:243], v[130:133], v[102:117]
	ds_read_b128 v[240:243], v207 offset:45760
	s_waitcnt lgkmcnt(9)
	v_mfma_f32_32x32x16_bf16 v[102:117], v[244:247], v[134:137], v[102:117]
	ds_read_b128 v[244:247], v207 offset:45792
	s_waitcnt lgkmcnt(9)
	v_mfma_f32_32x32x16_bf16 v[102:117], v[248:251], v[138:141], v[102:117]
	s_waitcnt lgkmcnt(8)
	v_mfma_f32_32x32x16_bf16 v[102:117], v[222:225], v[142:145], v[102:117]
	s_waitcnt lgkmcnt(7)
	v_mfma_f32_32x32x16_bf16 v[86:101], v[208:211], v[126:129], v[70:85]
	s_waitcnt lgkmcnt(6)
	v_mfma_f32_32x32x16_bf16 v[86:101], v[212:215], v[0:3], v[86:101]
	s_waitcnt lgkmcnt(5)
	v_mfma_f32_32x32x16_bf16 v[86:101], v[216:219], v[118:121], v[86:101]
	ds_read_b128 v[248:251], v204 offset:0
	ds_read_b128 v[222:225], v204 offset:32
	ds_read_b128 v[216:219], v204 offset:4608
	s_waitcnt lgkmcnt(7)
	v_mfma_f32_32x32x16_bf16 v[86:101], v[228:231], v[122:125], v[86:101]
	ds_read_b128 v[228:231], v204 offset:4640
	s_waitcnt lgkmcnt(7)
	v_mfma_f32_32x32x16_bf16 v[86:101], v[232:235], v[130:133], v[86:101]
	ds_read_b128 v[232:235], v204 offset:9216
	s_waitcnt lgkmcnt(7)
	v_mfma_f32_32x32x16_bf16 v[86:101], v[236:239], v[134:137], v[86:101]
	ds_read_b128 v[236:239], v204 offset:9248
	s_waitcnt lgkmcnt(7)
	v_mfma_f32_32x32x16_bf16 v[86:101], v[240:243], v[138:141], v[86:101]
	ds_read_b128 v[240:243], v204 offset:13824
	s_waitcnt lgkmcnt(7)
	v_mfma_f32_32x32x16_bf16 v[86:101], v[244:247], v[142:145], v[86:101]
	ds_read_b128 v[244:247], v204 offset:13856
	v_lshrrev_b64 v[208:209], v182, v[220:221]
	v_exp_f32_e32 v102, v102
	v_bfe_i32 v209, v208, 0, 1
	v_exp_f32_e32 v103, v103
	v_bfe_i32 v210, v208, 1, 1
	v_and_b32_e32 v102, v102, v209
	v_exp_f32_e32 v104, v104
	v_bfe_i32 v211, v208, 2, 1
	v_and_b32_e32 v103, v103, v210
	v_exp_f32_e32 v105, v105
	v_bfe_i32 v209, v208, 3, 1
	v_and_b32_e32 v104, v104, v211
	v_exp_f32_e32 v106, v106
	v_bfe_i32 v210, v208, 8, 1
	v_and_b32_e32 v105, v105, v209
	v_exp_f32_e32 v107, v107
	v_bfe_i32 v211, v208, 9, 1
	v_and_b32_e32 v106, v106, v210
	v_exp_f32_e32 v108, v108
	v_bfe_i32 v209, v208, 10, 1
	v_and_b32_e32 v107, v107, v211
	v_exp_f32_e32 v109, v109
	v_bfe_i32 v210, v208, 11, 1
	v_and_b32_e32 v108, v108, v209
	v_exp_f32_e32 v110, v110
	v_bfe_i32 v211, v208, 16, 1
	v_and_b32_e32 v109, v109, v210
	v_exp_f32_e32 v111, v111
	v_bfe_i32 v209, v208, 17, 1
	v_and_b32_e32 v110, v110, v211
	v_exp_f32_e32 v112, v112
	v_bfe_i32 v210, v208, 18, 1
	v_and_b32_e32 v111, v111, v209
	v_exp_f32_e32 v113, v113
	v_bfe_i32 v211, v208, 19, 1
	v_and_b32_e32 v112, v112, v210
	v_exp_f32_e32 v114, v114
	v_bfe_i32 v209, v208, 24, 1
	v_and_b32_e32 v113, v113, v211
	v_exp_f32_e32 v115, v115
	v_bfe_i32 v210, v208, 25, 1
	v_and_b32_e32 v114, v114, v209
	v_exp_f32_e32 v116, v116
	v_bfe_i32 v211, v208, 26, 1
	v_and_b32_e32 v115, v115, v210
	v_exp_f32_e32 v117, v117
	v_bfe_i32 v209, v208, 27, 1
	v_and_b32_e32 v116, v116, v211
	s_nop 0
	v_and_b32_e32 v117, v117, v209
	v_cvt_pk_bf16_f32 v208, v102, v103
	v_cvt_pk_bf16_f32 v209, v104, v105
	v_cvt_pk_bf16_f32 v210, v106, v107
	v_cvt_pk_bf16_f32 v211, v108, v109
	v_cvt_pk_bf16_f32 v212, v110, v111
	v_cvt_pk_bf16_f32 v213, v112, v113
	v_cvt_pk_bf16_f32 v214, v114, v115
	v_cvt_pk_bf16_f32 v215, v116, v117
	s_nop 1
	s_waitcnt lgkmcnt(7)
	v_mfma_f32_32x32x16_bf16 v[54:69], v[248:251], v[208:211], v[54:69]
	ds_read_b128 v[248:251], v204 offset:64
	v_add_f32_e32 v194, v194, v102
	v_add_f32_e32 v194, v103, v194
	s_waitcnt lgkmcnt(7)
	v_mfma_f32_32x32x16_bf16 v[54:69], v[222:225], v[212:215], v[54:69]
	ds_read_b128 v[222:225], v204 offset:96
	v_add_f32_e32 v194, v104, v194
	v_add_f32_e32 v194, v105, v194
	s_waitcnt lgkmcnt(7)
	v_mfma_f32_32x32x16_bf16 v[38:53], v[216:219], v[208:211], v[38:53]
	ds_read_b128 v[216:219], v204 offset:4672
	v_add_f32_e32 v194, v106, v194
	v_add_f32_e32 v194, v107, v194
	s_waitcnt lgkmcnt(7)
	v_mfma_f32_32x32x16_bf16 v[38:53], v[228:231], v[212:215], v[38:53]
	ds_read_b128 v[228:231], v204 offset:4704
	v_add_f32_e32 v194, v108, v194
	v_add_f32_e32 v194, v109, v194
	s_waitcnt lgkmcnt(7)
	v_mfma_f32_32x32x16_bf16 v[22:37], v[232:235], v[208:211], v[22:37]
	ds_read_b128 v[232:235], v204 offset:9280
	v_add_f32_e32 v194, v110, v194
	v_add_f32_e32 v194, v111, v194
	s_waitcnt lgkmcnt(7)
	v_mfma_f32_32x32x16_bf16 v[22:37], v[236:239], v[212:215], v[22:37]
	ds_read_b128 v[236:239], v204 offset:9312
	v_add_f32_e32 v194, v112, v194
	v_add_f32_e32 v194, v113, v194
	s_waitcnt lgkmcnt(7)
; #define LAS __attribute__((address_space(3)))
; __device__ __forceinline__ unsigned pk2(float lo, float hi) { f32x2_t v = {lo, hi}; bf16x2_t b = __builtin_convertvector(v, bf16x2_t); return __builtin_bit_cast(unsigned, b); }
; __device__ __forceinline__ void dsa_unit32(const Args& a, LAS unsigned char* lds, const LAS unsigned long long* maskl, int b, int qb, int tid, int wave, int lane) {
;     ...
;     auto compute = [&](int buf, int kt) {
;         const unsigned long long mw = maskl[l31 * 32 + kt];
;         const LAS bf16* Ks = (const LAS bf16*)(lds + buf * STG); const LAS bf16* Vs = (const LAS bf16*)(lds + buf * STG + KBYTES);
;         f32x16 S2[2];
; #pragma unroll
;         for (int kh = 0; kh < 2; ++kh) {
; #pragma unroll
;             for (int i = 0; i < 16; ++i) S2[kh][i] = negB;
;             __builtin_amdgcn_s_setprio(1);
; #pragma unroll
;             for (int ks = 0; ks < 8; ++ks) S2[kh] = mfma32(*(const LAS bf16x8*)(Ks + (32 * kh + l31) * KS + 16 * ks + 8 * hi), qf[ks], S2[kh]);
;             __builtin_amdgcn_s_setprio(0);
;         }
; #pragma unroll
;         for (int kh = 0; kh < 2; ++kh) {
;             const unsigned mh = (unsigned)(mw >> (32 * kh + 4 * hi));
;             float p[16];
; #pragma unroll
;             for (int i = 0; i < 16; ++i) { const float e = __builtin_amdgcn_exp2f(S2[kh][i]);
;                 const int keep = __builtin_amdgcn_sbfe((int)mh, 8 * (i >> 2) + (i & 3), 1);
;                 p[i] = __builtin_bit_cast(float, __builtin_bit_cast(int, e) & keep); l += p[i]; }
;             u32x4 w0, w1;
;             w0.x = pk2(p[0], p[1]); w0.y = pk2(p[2], p[3]); w0.z = pk2(p[4], p[5]); w0.w = pk2(p[6], p[7]);
;             w1.x = pk2(p[8], p[9]); w1.y = pk2(p[10], p[11]); w1.z = pk2(p[12], p[13]); w1.w = pk2(p[14], p[15]);
;             const bf16x8 pa = __builtin_bit_cast(bf16x8, w0), pb = __builtin_bit_cast(bf16x8, w1);
;             __builtin_amdgcn_s_setprio(1);
; #pragma unroll
;             for (int ct = 0; ct < 4; ++ct) {
;                 const LAS bf16* vr = Vs + (32 * ct + l31) * VS + 4 * hi + 32 * kh;
;                 O[ct] = mfma32(cat8(*(const LAS u32x2*)(vr), *(const LAS u32x2*)(vr + 8)), pa, O[ct]);
;                 O[ct] = mfma32(cat8(*(const LAS u32x2*)(vr + 16), *(const LAS u32x2*)(vr + 24)), pb, O[ct]);
;             }
;             __builtin_amdgcn_s_setprio(0);
;         }
	v_mfma_f32_32x32x16_bf16 v[6:21], v[240:243], v[208:211], v[6:21]
	ds_read_b128 v[240:243], v204 offset:13888
	v_add_f32_e32 v194, v114, v194
	v_add_f32_e32 v194, v115, v194
	s_waitcnt lgkmcnt(7)
	v_mfma_f32_32x32x16_bf16 v[6:21], v[244:247], v[212:215], v[6:21]
	ds_read_b128 v[244:247], v204 offset:13920
	v_add_f32_e32 v194, v116, v194
	v_add_f32_e32 v194, v117, v194
	v_lshrrev_b64 v[208:209], v184, v[220:221]
	v_exp_f32_e32 v86, v86
	v_bfe_i32 v209, v208, 0, 1
	v_exp_f32_e32 v87, v87
	v_bfe_i32 v210, v208, 1, 1
	v_and_b32_e32 v86, v86, v209
	v_exp_f32_e32 v88, v88
	v_bfe_i32 v211, v208, 2, 1
	v_and_b32_e32 v87, v87, v210
	v_exp_f32_e32 v89, v89
	v_bfe_i32 v209, v208, 3, 1
	v_and_b32_e32 v88, v88, v211
	v_exp_f32_e32 v90, v90
	v_bfe_i32 v210, v208, 8, 1
	v_and_b32_e32 v89, v89, v209
	v_exp_f32_e32 v91, v91
	v_bfe_i32 v211, v208, 9, 1
	v_and_b32_e32 v90, v90, v210
	v_exp_f32_e32 v92, v92
	v_bfe_i32 v209, v208, 10, 1
	v_and_b32_e32 v91, v91, v211
	v_exp_f32_e32 v93, v93
	v_bfe_i32 v210, v208, 11, 1
	v_and_b32_e32 v92, v92, v209
	v_exp_f32_e32 v94, v94
	v_bfe_i32 v211, v208, 16, 1
	v_and_b32_e32 v93, v93, v210
	v_exp_f32_e32 v95, v95
	v_bfe_i32 v209, v208, 17, 1
	v_and_b32_e32 v94, v94, v211
	v_exp_f32_e32 v96, v96
	v_bfe_i32 v210, v208, 18, 1
	v_and_b32_e32 v95, v95, v209
	v_exp_f32_e32 v97, v97
	v_bfe_i32 v211, v208, 19, 1
	v_and_b32_e32 v96, v96, v210
	v_exp_f32_e32 v98, v98
	v_bfe_i32 v209, v208, 24, 1
	v_and_b32_e32 v97, v97, v211
	v_exp_f32_e32 v99, v99
	v_bfe_i32 v210, v208, 25, 1
	v_and_b32_e32 v98, v98, v209
	v_exp_f32_e32 v100, v100
	v_bfe_i32 v211, v208, 26, 1
	v_and_b32_e32 v99, v99, v210
	v_exp_f32_e32 v101, v101
	v_bfe_i32 v209, v208, 27, 1
	v_and_b32_e32 v100, v100, v211
	s_nop 0
	v_and_b32_e32 v101, v101, v209
	v_cvt_pk_bf16_f32 v208, v86, v87
	v_cvt_pk_bf16_f32 v209, v88, v89
	v_cvt_pk_bf16_f32 v210, v90, v91
	v_cvt_pk_bf16_f32 v211, v92, v93
	v_cvt_pk_bf16_f32 v212, v94, v95
	v_cvt_pk_bf16_f32 v213, v96, v97
	v_cvt_pk_bf16_f32 v214, v98, v99
	v_cvt_pk_bf16_f32 v215, v100, v101
	s_nop 1
	s_waitcnt lgkmcnt(7)
	v_mfma_f32_32x32x16_bf16 v[54:69], v[248:251], v[208:211], v[54:69]
	v_add_f32_e32 v194, v194, v86
	v_add_f32_e32 v194, v87, v194
	s_waitcnt lgkmcnt(6)
	v_mfma_f32_32x32x16_bf16 v[54:69], v[222:225], v[212:215], v[54:69]
	v_add_f32_e32 v194, v88, v194
	v_add_f32_e32 v194, v89, v194
	s_waitcnt lgkmcnt(5)
	v_mfma_f32_32x32x16_bf16 v[38:53], v[216:219], v[208:211], v[38:53]
	v_add_f32_e32 v194, v90, v194
	v_add_f32_e32 v194, v91, v194
	s_waitcnt lgkmcnt(4)
	v_mfma_f32_32x32x16_bf16 v[38:53], v[228:231], v[212:215], v[38:53]
	v_add_f32_e32 v194, v92, v194
	v_add_f32_e32 v194, v93, v194
	s_waitcnt lgkmcnt(3)
	v_mfma_f32_32x32x16_bf16 v[22:37], v[232:235], v[208:211], v[22:37]
	v_add_f32_e32 v194, v94, v194
	v_add_f32_e32 v194, v95, v194
	s_waitcnt lgkmcnt(2)
	v_mfma_f32_32x32x16_bf16 v[22:37], v[236:239], v[212:215], v[22:37]
	v_add_f32_e32 v194, v96, v194
	v_add_f32_e32 v194, v97, v194
	s_waitcnt lgkmcnt(1)
	v_mfma_f32_32x32x16_bf16 v[6:21], v[240:243], v[208:211], v[6:21]
	v_add_f32_e32 v194, v98, v194
	v_add_f32_e32 v194, v99, v194
	s_waitcnt lgkmcnt(0)
	v_mfma_f32_32x32x16_bf16 v[6:21], v[244:247], v[212:215], v[6:21]
	v_add_f32_e32 v194, v100, v194
	v_add_f32_e32 v194, v101, v194
	s_branch .Ldsa_J1
.Ldsa_B1:
	ds_read_b64 v[220:221], v206
	v_add_u32_e32 v207, v202, v180
	ds_read_b128 v[216:219], v207 offset:36864
	ds_read_b128 v[228:231], v207 offset:36896
	ds_read_b128 v[232:235], v207 offset:36928
	ds_read_b128 v[236:239], v207 offset:36960
	ds_read_b128 v[240:243], v207 offset:36992
	ds_read_b128 v[244:247], v207 offset:37024
	ds_read_b128 v[248:251], v207 offset:37056
	ds_read_b128 v[222:225], v207 offset:37088
	s_waitcnt lgkmcnt(7)
	v_mfma_f32_32x32x16_bf16 v[102:117], v[216:219], v[126:129], v[70:85]
	ds_read_b128 v[216:219], v207 offset:45568
	s_waitcnt lgkmcnt(7)
	v_mfma_f32_32x32x16_bf16 v[102:117], v[228:231], v[0:3], v[102:117]
	ds_read_b128 v[228:231], v207 offset:45600
	s_waitcnt lgkmcnt(7)
	v_mfma_f32_32x32x16_bf16 v[102:117], v[232:235], v[118:121], v[102:117]
	ds_read_b128 v[232:235], v207 offset:45632
	s_waitcnt lgkmcnt(7)
	v_mfma_f32_32x32x16_bf16 v[102:117], v[236:239], v[122:125], v[102:117]
	ds_read_b128 v[236:239], v207 offset:45664
	s_waitcnt lgkmcnt(7)
	v_mfma_f32_32x32x16_bf16 v[102:117], v[240:243], v[130:133], v[102:117]
	ds_read_b128 v[240:243], v207 offset:45696
	s_waitcnt lgkmcnt(7)
	v_mfma_f32_32x32x16_bf16 v[102:117], v[244:247], v[134:137], v[102:117]
	ds_read_b128 v[244:247], v207 offset:45728
	s_waitcnt lgkmcnt(7)
	v_mfma_f32_32x32x16_bf16 v[102:117], v[248:251], v[138:141], v[102:117]
	ds_read_b128 v[248:251], v207 offset:45760
	s_waitcnt lgkmcnt(7)
	v_mfma_f32_32x32x16_bf16 v[102:117], v[222:225], v[142:145], v[102:117]
	ds_read_b128 v[222:225], v207 offset:45792
	s_nop 7
	s_nop 3
	v_lshrrev_b64 v[208:209], v182, v[220:221]
	v_exp_f32_e32 v102, v102
	v_bfe_i32 v209, v208, 0, 1
	v_exp_f32_e32 v103, v103
	v_bfe_i32 v210, v208, 1, 1
	v_and_b32_e32 v102, v102, v209
	v_exp_f32_e32 v104, v104
	v_bfe_i32 v211, v208, 2, 1
	v_and_b32_e32 v103, v103, v210
	v_exp_f32_e32 v105, v105
	v_bfe_i32 v209, v208, 3, 1
	v_and_b32_e32 v104, v104, v211
	v_exp_f32_e32 v106, v106
	v_bfe_i32 v210, v208, 8, 1
	v_and_b32_e32 v105, v105, v209
	v_exp_f32_e32 v107, v107
	v_bfe_i32 v211, v208, 9, 1
	v_and_b32_e32 v106, v106, v210
	v_exp_f32_e32 v108, v108
	v_bfe_i32 v209, v208, 10, 1
	v_and_b32_e32 v107, v107, v211
	v_exp_f32_e32 v109, v109
	v_bfe_i32 v210, v208, 11, 1
	v_and_b32_e32 v108, v108, v209
	v_exp_f32_e32 v110, v110
	v_bfe_i32 v211, v208, 16, 1
	v_and_b32_e32 v109, v109, v210
	v_exp_f32_e32 v111, v111
	v_bfe_i32 v209, v208, 17, 1
	v_and_b32_e32 v110, v110, v211
	v_exp_f32_e32 v112, v112
	v_bfe_i32 v210, v208, 18, 1
	v_and_b32_e32 v111, v111, v209
	v_exp_f32_e32 v113, v113
	v_bfe_i32 v211, v208, 19, 1
	v_and_b32_e32 v112, v112, v210
	v_exp_f32_e32 v114, v114
	v_bfe_i32 v209, v208, 24, 1
	v_and_b32_e32 v113, v113, v211
	v_exp_f32_e32 v115, v115
	v_bfe_i32 v210, v208, 25, 1
	v_and_b32_e32 v114, v114, v209
	v_exp_f32_e32 v116, v116
	v_bfe_i32 v211, v208, 26, 1
	v_and_b32_e32 v115, v115, v210
	v_exp_f32_e32 v117, v117
	v_bfe_i32 v209, v208, 27, 1
	v_and_b32_e32 v116, v116, v211
	s_nop 0
	v_and_b32_e32 v117, v117, v209
	v_cvt_pk_bf16_f32 v208, v102, v103
	v_cvt_pk_bf16_f32 v209, v104, v105
	v_cvt_pk_bf16_f32 v210, v106, v107
	v_cvt_pk_bf16_f32 v211, v108, v109
	v_cvt_pk_bf16_f32 v212, v110, v111
	v_cvt_pk_bf16_f32 v213, v112, v113
	v_cvt_pk_bf16_f32 v214, v114, v115
	v_cvt_pk_bf16_f32 v215, v116, v117
	s_waitcnt lgkmcnt(7)
; #define LAS __attribute__((address_space(3)))
; __device__ __forceinline__ unsigned pk2(float lo, float hi) { f32x2_t v = {lo, hi}; bf16x2_t b = __builtin_convertvector(v, bf16x2_t); return __builtin_bit_cast(unsigned, b); }
; __device__ __forceinline__ void dsa_unit32(const Args& a, LAS unsigned char* lds, const LAS unsigned long long* maskl, int b, int qb, int tid, int wave, int lane) {
;     ...
;     auto compute = [&](int buf, int kt) {
;         const unsigned long long mw = maskl[l31 * 32 + kt];
;         const LAS bf16* Ks = (const LAS bf16*)(lds + buf * STG); const LAS bf16* Vs = (const LAS bf16*)(lds + buf * STG + KBYTES);
;         f32x16 S2[2];
; #pragma unroll
;         for (int kh = 0; kh < 2; ++kh) {
; #pragma unroll
;             for (int i = 0; i < 16; ++i) S2[kh][i] = negB;
;             __builtin_amdgcn_s_setprio(1);
; #pragma unroll
;             for (int ks = 0; ks < 8; ++ks) S2[kh] = mfma32(*(const LAS bf16x8*)(Ks + (32 * kh + l31) * KS + 16 * ks + 8 * hi), qf[ks], S2[kh]);
;             __builtin_amdgcn_s_setprio(0);
;         }
; #pragma unroll
;         for (int kh = 0; kh < 2; ++kh) {
;             const unsigned mh = (unsigned)(mw >> (32 * kh + 4 * hi));
;             float p[16];
; #pragma unroll
;             for (int i = 0; i < 16; ++i) { const float e = __builtin_amdgcn_exp2f(S2[kh][i]);
;                 const int keep = __builtin_amdgcn_sbfe((int)mh, 8 * (i >> 2) + (i & 3), 1);
;                 p[i] = __builtin_bit_cast(float, __builtin_bit_cast(int, e) & keep); l += p[i]; }
;             u32x4 w0, w1;
;             w0.x = pk2(p[0], p[1]); w0.y = pk2(p[2], p[3]); w0.z = pk2(p[4], p[5]); w0.w = pk2(p[6], p[7]);
;             w1.x = pk2(p[8], p[9]); w1.y = pk2(p[10], p[11]); w1.z = pk2(p[12], p[13]); w1.w = pk2(p[14], p[15]);
;             const bf16x8 pa = __builtin_bit_cast(bf16x8, w0), pb = __builtin_bit_cast(bf16x8, w1);
;             __builtin_amdgcn_s_setprio(1);
; #pragma unroll
;             for (int ct = 0; ct < 4; ++ct) {
;                 const LAS bf16* vr = Vs + (32 * ct + l31) * VS + 4 * hi + 32 * kh;
;                 O[ct] = mfma32(cat8(*(const LAS u32x2*)(vr), *(const LAS u32x2*)(vr + 8)), pa, O[ct]);
;                 O[ct] = mfma32(cat8(*(const LAS u32x2*)(vr + 16), *(const LAS u32x2*)(vr + 24)), pb, O[ct]);
;             }
;             __builtin_amdgcn_s_setprio(0);
;         }
	v_mfma_f32_32x32x16_bf16 v[86:101], v[216:219], v[126:129], v[70:85]
	ds_read_b128 v[216:219], v204 offset:0
	s_waitcnt lgkmcnt(7)
	v_mfma_f32_32x32x16_bf16 v[86:101], v[228:231], v[0:3], v[86:101]
	ds_read_b128 v[228:231], v204 offset:32
	s_waitcnt lgkmcnt(7)
	v_mfma_f32_32x32x16_bf16 v[86:101], v[232:235], v[118:121], v[86:101]
	ds_read_b128 v[232:235], v204 offset:4608
	s_waitcnt lgkmcnt(7)
	v_mfma_f32_32x32x16_bf16 v[86:101], v[236:239], v[122:125], v[86:101]
	ds_read_b128 v[236:239], v204 offset:4640
	s_waitcnt lgkmcnt(7)
	v_mfma_f32_32x32x16_bf16 v[86:101], v[240:243], v[130:133], v[86:101]
	ds_read_b128 v[240:243], v204 offset:9216
	s_waitcnt lgkmcnt(7)
	v_mfma_f32_32x32x16_bf16 v[86:101], v[244:247], v[134:137], v[86:101]
	ds_read_b128 v[244:247], v204 offset:9248
	s_waitcnt lgkmcnt(7)
	v_mfma_f32_32x32x16_bf16 v[86:101], v[248:251], v[138:141], v[86:101]
	ds_read_b128 v[248:251], v204 offset:13824
	s_waitcnt lgkmcnt(7)
	v_mfma_f32_32x32x16_bf16 v[86:101], v[222:225], v[142:145], v[86:101]
	ds_read_b128 v[222:225], v204 offset:13856
	v_add_f32_e32 v194, v194, v102
	v_add_f32_e32 v194, v103, v194
	v_add_f32_e32 v194, v104, v194
	v_add_f32_e32 v194, v105, v194
	v_add_f32_e32 v194, v106, v194
	v_add_f32_e32 v194, v107, v194
	v_add_f32_e32 v194, v108, v194
	v_add_f32_e32 v194, v109, v194
	v_add_f32_e32 v194, v110, v194
	v_add_f32_e32 v194, v111, v194
	v_add_f32_e32 v194, v112, v194
	v_add_f32_e32 v194, v113, v194
	v_add_f32_e32 v194, v114, v194
	v_add_f32_e32 v194, v115, v194
	v_add_f32_e32 v194, v116, v194
	v_add_f32_e32 v194, v117, v194
	v_lshrrev_b64 v[110:111], v184, v[220:221]
	v_exp_f32_e32 v86, v86
	v_bfe_i32 v111, v110, 0, 1
	v_exp_f32_e32 v87, v87
	v_bfe_i32 v112, v110, 1, 1
	v_and_b32_e32 v86, v86, v111
	v_exp_f32_e32 v88, v88
	v_bfe_i32 v113, v110, 2, 1
	v_and_b32_e32 v87, v87, v112
	v_exp_f32_e32 v89, v89
	v_bfe_i32 v111, v110, 3, 1
	v_and_b32_e32 v88, v88, v113
	v_exp_f32_e32 v90, v90
	v_bfe_i32 v112, v110, 8, 1
	v_and_b32_e32 v89, v89, v111
	v_exp_f32_e32 v91, v91
	v_bfe_i32 v113, v110, 9, 1
	v_and_b32_e32 v90, v90, v112
	v_exp_f32_e32 v92, v92
	v_bfe_i32 v111, v110, 10, 1
	v_and_b32_e32 v91, v91, v113
	v_exp_f32_e32 v93, v93
	v_bfe_i32 v112, v110, 11, 1
	v_and_b32_e32 v92, v92, v111
	v_exp_f32_e32 v94, v94
	v_bfe_i32 v113, v110, 16, 1
	v_and_b32_e32 v93, v93, v112
	v_exp_f32_e32 v95, v95
	v_bfe_i32 v111, v110, 17, 1
	v_and_b32_e32 v94, v94, v113
	v_exp_f32_e32 v96, v96
	v_bfe_i32 v112, v110, 18, 1
	v_and_b32_e32 v95, v95, v111
	v_exp_f32_e32 v97, v97
	v_bfe_i32 v113, v110, 19, 1
	v_and_b32_e32 v96, v96, v112
	v_exp_f32_e32 v98, v98
	v_bfe_i32 v111, v110, 24, 1
	v_and_b32_e32 v97, v97, v113
	v_exp_f32_e32 v99, v99
	v_bfe_i32 v112, v110, 25, 1
	v_and_b32_e32 v98, v98, v111
	v_exp_f32_e32 v100, v100
	v_bfe_i32 v113, v110, 26, 1
	v_and_b32_e32 v99, v99, v112
	v_exp_f32_e32 v101, v101
	v_bfe_i32 v111, v110, 27, 1
	v_and_b32_e32 v100, v100, v113
	s_nop 0
	v_and_b32_e32 v101, v101, v111
	v_cvt_pk_bf16_f32 v102, v86, v87
	v_cvt_pk_bf16_f32 v103, v88, v89
	v_cvt_pk_bf16_f32 v104, v90, v91
	v_cvt_pk_bf16_f32 v105, v92, v93
	v_cvt_pk_bf16_f32 v106, v94, v95
	v_cvt_pk_bf16_f32 v107, v96, v97
	v_cvt_pk_bf16_f32 v108, v98, v99
	v_cvt_pk_bf16_f32 v109, v100, v101
	s_nop 1
	s_waitcnt lgkmcnt(7)
	v_mfma_f32_32x32x16_bf16 v[54:69], v[216:219], v[208:211], v[54:69]
	ds_read_b128 v[216:219], v204 offset:64
	s_waitcnt lgkmcnt(7)
	v_mfma_f32_32x32x16_bf16 v[54:69], v[228:231], v[212:215], v[54:69]
	ds_read_b128 v[228:231], v204 offset:96
	s_waitcnt lgkmcnt(7)
	v_mfma_f32_32x32x16_bf16 v[38:53], v[232:235], v[208:211], v[38:53]
	ds_read_b128 v[232:235], v204 offset:4672
	s_waitcnt lgkmcnt(7)
	v_mfma_f32_32x32x16_bf16 v[38:53], v[236:239], v[212:215], v[38:53]
	ds_read_b128 v[236:239], v204 offset:4704
	s_waitcnt lgkmcnt(7)
	v_mfma_f32_32x32x16_bf16 v[22:37], v[240:243], v[208:211], v[22:37]
	ds_read_b128 v[240:243], v204 offset:9280
	s_waitcnt lgkmcnt(7)
	v_mfma_f32_32x32x16_bf16 v[22:37], v[244:247], v[212:215], v[22:37]
	ds_read_b128 v[244:247], v204 offset:9312
	s_waitcnt lgkmcnt(7)
	v_mfma_f32_32x32x16_bf16 v[6:21], v[248:251], v[208:211], v[6:21]
	ds_read_b128 v[248:251], v204 offset:13888
	s_waitcnt lgkmcnt(7)
	v_mfma_f32_32x32x16_bf16 v[6:21], v[222:225], v[212:215], v[6:21]
	ds_read_b128 v[222:225], v204 offset:13920
	s_waitcnt lgkmcnt(7)
	v_mfma_f32_32x32x16_bf16 v[54:69], v[216:219], v[102:105], v[54:69]
	v_add_f32_e32 v194, v194, v86
	v_add_f32_e32 v194, v87, v194
	s_waitcnt lgkmcnt(6)
	v_mfma_f32_32x32x16_bf16 v[54:69], v[228:231], v[106:109], v[54:69]
	v_add_f32_e32 v194, v88, v194
	v_add_f32_e32 v194, v89, v194
	s_waitcnt lgkmcnt(5)
	v_mfma_f32_32x32x16_bf16 v[38:53], v[232:235], v[102:105], v[38:53]
	v_add_f32_e32 v194, v90, v194
	v_add_f32_e32 v194, v91, v194
	s_waitcnt lgkmcnt(4)
	v_mfma_f32_32x32x16_bf16 v[38:53], v[236:239], v[106:109], v[38:53]
	v_add_f32_e32 v194, v92, v194
	v_add_f32_e32 v194, v93, v194
	s_waitcnt lgkmcnt(3)
	v_mfma_f32_32x32x16_bf16 v[22:37], v[240:243], v[102:105], v[22:37]
	v_add_f32_e32 v194, v94, v194
	v_add_f32_e32 v194, v95, v194
	s_waitcnt lgkmcnt(2)
	v_mfma_f32_32x32x16_bf16 v[22:37], v[244:247], v[106:109], v[22:37]
	v_add_f32_e32 v194, v96, v194
	v_add_f32_e32 v194, v97, v194
	s_waitcnt lgkmcnt(1)
	v_mfma_f32_32x32x16_bf16 v[6:21], v[248:251], v[102:105], v[6:21]
	v_add_f32_e32 v194, v98, v194
	v_add_f32_e32 v194, v99, v194
	s_waitcnt lgkmcnt(0)
	v_mfma_f32_32x32x16_bf16 v[6:21], v[222:225], v[106:109], v[6:21]
	v_add_f32_e32 v194, v100, v194
	v_add_f32_e32 v194, v101, v194

; __device__ __forceinline__ unsigned xb_ld(unsigned* p)              { return __hip_atomic_load(p, __ATOMIC_RELAXED, __HIP_MEMORY_SCOPE_AGENT); }
; __device__ __forceinline__ unsigned xb_add(unsigned* p, unsigned v) { return __hip_atomic_fetch_add(p, v, __ATOMIC_RELAXED, __HIP_MEMORY_SCOPE_AGENT); }
; #define XB_SPIN(cond, bar) do { unsigned _sp = 0; while (cond) { __builtin_amdgcn_s_sleep(1); \
;     if ((++_sp & 255u) == 0u) { if (xb_ld(&(bar)[XB_TMO])) break; if (_sp > XB_SPIN_CAP) { atomicAdd(&(bar)[XB_TMO], 1u); break; } } } } while (0)
; __device__ __forceinline__ void xcd_barrier(const XcdBarrier& b) {
;     asm volatile("s_waitcnt vmcnt(0)" ::: "memory");
;     __syncthreads();
;     if (threadIdx.x == 0) {
;         unsigned* bar = b.bar;
;         __builtin_amdgcn_s_waitcnt(0);
;         unsigned nloc = b.st[0], nx = b.st[1];
;         if (nloc == 0u) { xcd_barrier_complete(bar, b.x, nloc, nx); b.st[0] = nloc; b.st[1] = nx; }
;         const unsigned old = xb_add(&bar[XB_XSUB(b.x)], 1u);
;         const unsigned gen = old / nloc;
;         if (old + 1u == (gen + 1u) * nloc) {
;             __builtin_amdgcn_fence(__ATOMIC_RELEASE, "agent");
;             asm volatile("s_waitcnt vmcnt(0)" ::: "memory");
;             const unsigned og = xb_add(&bar[XB_TOP], 1u);
;             const unsigned tg = og / nx;
;             if (og + 1u == (tg + 1u) * nx) xb_add(&bar[XB_TOPGEN], 1u);
;             else XB_SPIN(xb_ld(&bar[XB_TOPGEN]) == tg, bar);
;             __builtin_amdgcn_fence(__ATOMIC_ACQUIRE, "agent");
;             xb_add(&bar[XB_XGEN(b.x)], 1u);
;             asm volatile("s_waitcnt vmcnt(0)" ::: "memory");
;         } else {
;             XB_SPIN(xb_ld(&bar[XB_XGEN(b.x)]) == gen, bar);
;             __builtin_amdgcn_fence(__ATOMIC_ACQUIRE, "agent");
;             asm volatile("s_waitcnt vmcnt(0)" ::: "memory");
;         }
;     }
;     __syncthreads();
; }
.LBB0_1312:
	s_setprio 0
	s_getreg_b32 s2, hwreg(HW_REG_XCC_ID, 0, 4)
	s_waitcnt vmcnt(0)
	s_barrier
	s_mov_b64 s[0:1], exec
	v_readlane_b32 s4, v254, 2
	v_readlane_b32 s5, v254, 3
	v_readlane_b32 s72, v254, 13
	v_readlane_b32 s74, v254, 11
	v_readlane_b32 s78, v254, 7
	s_and_b64 s[4:5], s[0:1], s[4:5]
	v_readlane_b32 s73, v254, 14
	v_readlane_b32 s75, v254, 12
	v_readlane_b32 s76, v254, 10
	v_readlane_b32 s77, v254, 15
	v_readlane_b32 s79, v254, 8
	v_readlane_b32 s70, v254, 9
	s_mov_b64 exec, s[4:5]
	s_cbranch_execz .LBB0_1356
	s_add_i32 s3, 0, 0x200c0
	v_mov_b32_e32 v0, s3
	s_waitcnt vmcnt(0) expcnt(0) lgkmcnt(0)
	ds_read_b32 v2, v0
	s_add_i32 s3, 0, 0x200c4
	v_mov_b32_e32 v0, s3
	ds_read_b32 v0, v0
	s_and_b32 s33, s2, 15
	s_waitcnt lgkmcnt(1)
	v_cmp_ne_u32_e32 vcc, 0, v2
	s_cbranch_vccnz .LBB0_1327
	v_readlane_b32 s2, v254, 0
	v_readlane_b32 s3, v254, 1
	s_load_dwordx2 s[4:5], s[2:3], 0x4
	s_add_u32 s2, s72, 0xa0a200
	s_addc_u32 s3, s73, 0
	s_add_u32 s6, s72, 0xa0a400
	s_addc_u32 s7, s73, 0
	s_add_u32 s8, s72, 0xa0a500
	s_addc_u32 s9, s73, 0
	s_add_u32 s10, s72, 0xa0a600
	s_addc_u32 s11, s73, 0
	s_add_u32 s12, s72, 0xa0a700
	s_addc_u32 s13, s73, 0
	s_add_u32 s14, s72, 0xa0a800
	s_addc_u32 s15, s73, 0
	s_add_u32 s16, s72, 0xa0a900
	s_addc_u32 s17, s73, 0
	s_add_u32 s18, s72, 0xa0aa00
	s_addc_u32 s19, s73, 0
	s_add_u32 s20, s72, 0xa0ab00
	s_addc_u32 s21, s73, 0
	s_add_u32 s24, s72, 0xa0ac00
	s_addc_u32 s25, s73, 0
	s_add_u32 s26, s72, 0xa0ad00
	s_addc_u32 s27, s73, 0
	s_add_u32 s28, s72, 0xa0ae00
	s_addc_u32 s29, s73, 0
	s_add_u32 s30, s72, 0xa0af00
	s_addc_u32 s31, s73, 0
	s_add_u32 s34, s72, 0xa0b000
	s_addc_u32 s35, s73, 0
	s_add_u32 s36, s72, 0xa0b100
	s_addc_u32 s37, s73, 0
	s_add_u32 s38, s72, 0xa0b200
	s_addc_u32 s39, s73, 0
	s_add_u32 s40, s72, 0xa0b300
	s_waitcnt lgkmcnt(0)
	s_mul_i32 s22, s4, s76
	s_addc_u32 s41, s73, 0
	s_mul_i32 s22, s22, s5
	s_mov_b32 s23, 1
	s_mov_b64 s[4:5], 0
	v_mov_b64_e32 v[0:1], s[6:7]
	v_mov_b64_e32 v[2:3], s[8:9]
	v_mov_b64_e32 v[4:5], s[10:11]
	v_mov_b64_e32 v[6:7], s[12:13]
	v_mov_b64_e32 v[8:9], s[14:15]
	v_mov_b64_e32 v[10:11], s[16:17]
	v_mov_b64_e32 v[12:13], s[18:19]
	v_mov_b64_e32 v[14:15], s[20:21]
	v_mov_b64_e32 v[16:17], s[24:25]
	v_mov_b64_e32 v[18:19], s[26:27]
	v_mov_b64_e32 v[20:21], s[28:29]
	v_mov_b64_e32 v[22:23], s[30:31]
	v_mov_b64_e32 v[24:25], s[34:35]
	v_mov_b64_e32 v[26:27], s[36:37]
	v_mov_b64_e32 v[28:29], s[38:39]
	v_mov_b64_e32 v[30:31], s[40:41]
	s_branch .LBB0_1317
